# final RMSNorm loop: same counted-wait move as the other norm loops
# speedup vs baseline: 1.0117x; 1.0001x over previous
; template <bool F32OUT> __device__ __forceinline__ void norm_rows16(const bf16_t* X, const float* __restrict__ g, void* out, int rows) {
;     int bid_ = blockIdx.x, gdim_ = gridDim.x; asm volatile("" : "+s"(bid_), "+s"(gdim_));
;     int tix_ = threadIdx.x; asm volatile("" : "+v"(tix_));
;     const int lane = tix_ & 63, gw = __builtin_amdgcn_readfirstlane(bid_ * 8 + (tix_ >> 6)), GW = gdim_ * 8;
;     float4 ga[4], gb[4];
; #pragma unroll
;     for (int i = 0; i < 4; ++i) { ga[i] = *(const float4*)(g + 8 * lane + 512 * i); gb[i] = *(const float4*)(g + 8 * lane + 512 * i + 4); }
;     const int xl_ = bid_ & 7, chunk_ = rows >> 3, GWx = GW >> 3;
;     const int rend = chunk_ * (xl_ + 1);
;     int row = chunk_ * xl_ + ((bid_ >> 3) * 8 + (gw - bid_ * 8)); u32x4 x[4];
;     if (row < rend) {
; #pragma unroll
;         for (int i = 0; i < 4; ++i) x[i] = *(const u32x4*)(X + (size_t)row * DM + 8 * lane + 512 * i); }
;     while (row < rend) {
;         const int nrow = row + GWx; u32x4 xn[4];
;         if (nrow < rend) {
; #pragma unroll
;             for (int i = 0; i < 4; ++i) xn[i] = *(const u32x4*)(X + (size_t)nrow * DM + 8 * lane + 512 * i); }
.LBB0_2111:
	s_or_b64 exec, exec, s[4:5]
	s_mov_b32 s3, s40
	s_mov_b32 s4, s2
	s_waitcnt lgkmcnt(0)
	s_barrier
	s_lshl_b32 s11, s2, 3
	v_ashrrev_i32_e32 v0, 6, v228
	v_add_u32_e32 v0, s11, v0
	s_and_b32 s12, s2, -8
	v_readfirstlane_b32 s13, v0
	s_sub_i32 s3, s13, s11
	s_add_i32 s3, s3, s12
	s_cmpk_gt_i32 s3, 0x7ff
	s_cbranch_scc1 .LBB0_2116
	s_load_dwordx4 s[4:7], s[0:1], 0x98
	s_load_dwordx2 s[8:9], s[0:1], 0xa8
	v_lshlrev_b32_e32 v0, 3, v228
	v_and_b32_e32 v38, 0x1f8, v0
	v_lshlrev_b32_e32 v0, 2, v38
	v_mov_b32_e32 v1, 0
	s_waitcnt lgkmcnt(0)
	v_lshl_add_u64 v[2:3], s[4:5], 0, v[0:1]
	s_movk_i32 s0, 0x1000
	global_load_dwordx4 v[4:7], v0, s[4:5] offset:16
	global_load_dwordx4 v[8:11], v0, s[4:5]
	global_load_dwordx4 v[12:15], v0, s[4:5] offset:2064
	global_load_dwordx4 v[16:19], v0, s[4:5] offset:2048
	s_mov_b64 s[4:5], 0x1000
	v_add_co_u32_e32 v36, vcc, s0, v2
	s_mov_b64 s[0:1], 0x1800
	v_lshl_add_u64 v[28:29], v[2:3], 0, s[4:5]
	v_addc_co_u32_e32 v37, vcc, 0, v3, vcc
	v_lshl_add_u64 v[2:3], v[2:3], 0, s[0:1]
	s_lshl_b32 s0, s2, 11
	s_and_b32 s16, s0, 0x3800
	s_add_i32 s0, s3, s16
	s_ashr_i32 s1, s0, 31
	s_add_i32 s10, s16, 0x800
	s_lshl_b64 s[2:3], s[0:1], 12
	s_add_u32 s2, s8, s2
	s_addc_u32 s3, s9, s3
	v_lshlrev_b32_e32 v0, 1, v38
	global_load_dwordx4 v[20:23], v[36:37], off
	global_load_dwordx4 v[24:27], v[28:29], off offset:16
	s_nop 0
	global_load_dwordx4 v[28:31], v[36:37], off offset:2048
	global_load_dwordx4 v[32:35], v[2:3], off offset:16
	v_lshl_add_u64 v[2:3], s[2:3], 0, v[0:1]
	s_mov_b64 s[14:15], 0x2dd24000
	s_mov_b32 s2, 0x2dd24000
	v_lshl_add_u64 v[36:37], v[2:3], 0, s[14:15]
	v_add_co_u32_e32 v2, vcc, s2, v2
	v_mbcnt_hi_u32_b32 v0, -1, v229
	s_nop 0
	v_addc_co_u32_e32 v3, vcc, 0, v3, vcc
	global_load_dwordx4 v[56:59], v[36:37], off offset:1024
	global_load_dwordx4 v[52:55], v[36:37], off offset:2048
	global_load_dwordx4 v[60:63], v[2:3], off
	global_load_dwordx4 v[48:51], v[36:37], off offset:3072
	v_and_b32_e32 v2, 64, v0
	v_add_u32_e32 v2, 64, v2
	v_xor_b32_e32 v3, 32, v0
	v_cmp_lt_i32_e32 vcc, v3, v2
	s_lshl_b64 s[2:3], s[0:1], 13
	s_add_u32 s2, s6, s2
	v_cndmask_b32_e32 v3, v0, v3, vcc
	v_lshlrev_b32_e32 v68, 2, v3
	v_xor_b32_e32 v3, 16, v0
	v_cmp_lt_i32_e32 vcc, v3, v2
	v_and_b32_e32 v36, 63, v228
	s_addc_u32 s3, s7, s3
	v_cndmask_b32_e32 v3, v0, v3, vcc
	v_lshlrev_b32_e32 v69, 2, v3
	v_xor_b32_e32 v3, 8, v0
	v_cmp_lt_i32_e32 vcc, v3, v2
	s_add_i32 s1, s40, s13
	s_add_i32 s1, s1, s16
	v_cndmask_b32_e32 v3, v0, v3, vcc
	v_lshlrev_b32_e32 v70, 2, v3
	v_xor_b32_e32 v3, 4, v0
	v_cmp_lt_i32_e32 vcc, v3, v2
	s_add_i32 s1, s1, s12
	s_ashr_i32 s41, s40, 31
	v_cndmask_b32_e32 v3, v0, v3, vcc
	v_lshlrev_b32_e32 v71, 2, v3
	v_xor_b32_e32 v3, 2, v0
	v_cmp_lt_i32_e32 vcc, v3, v2
	v_mov_b32_e32 v74, 0x358637bd
	v_mov_b32_e32 v37, v1
	v_cndmask_b32_e32 v3, v0, v3, vcc
	v_lshlrev_b32_e32 v72, 2, v3
	v_xor_b32_e32 v3, 1, v0
	v_cmp_lt_i32_e32 vcc, v3, v2
	v_mov_b32_e32 v38, v1
	v_mov_b32_e32 v39, v1
	v_cndmask_b32_e32 v0, v0, v3, vcc
	v_lshlrev_b32_e32 v73, 2, v0
	v_lshlrev_b32_e32 v0, 5, v36
	v_lshl_add_u64 v[2:3], s[2:3], 0, v[0:1]
	v_lshl_add_u64 v[64:65], v[2:3], 0, s[4:5]
	s_sub_i32 s4, s1, s11
	s_ashr_i32 s5, s4, 31
	s_lshl_b64 s[2:3], s[40:41], 13
	s_lshl_b64 s[4:5], s[4:5], 12
	s_add_u32 s4, s8, s4
	v_lshlrev_b32_e32 v0, 4, v36
	s_addc_u32 s5, s9, s5
	v_lshl_add_u64 v[2:3], s[4:5], 0, v[0:1]
	v_lshl_add_u64 v[66:67], v[2:3], 0, s[14:15]
	s_lshl_b64 s[4:5], s[40:41], 12
	s_mov_b32 s1, 0x800000
	v_mov_b32_e32 v0, v1
	v_mov_b32_e32 v2, v1
	v_mov_b32_e32 v3, v1
	v_mov_b32_e32 v36, v1
	v_mov_b32_e32 v40, v1
	v_mov_b32_e32 v41, v1
	v_mov_b32_e32 v42, v1
	v_mov_b32_e32 v43, v1
	v_mov_b32_e32 v44, v1
	v_mov_b32_e32 v45, v1
	v_mov_b32_e32 v46, v1
	v_mov_b32_e32 v47, v1
	s_waitcnt vmcnt(0)
	s_branch .LBB0_2114
; __device__ __forceinline__ unsigned cvt_pk_bf16(float lo, float hi) { unsigned r; asm volatile("v_cvt_pk_bf16_f32 %0, %1, %2" : "=v"(r) : "v"(lo), "v"(hi)); return r; }
; __device__ __forceinline__ float bflo(unsigned w) { return __uint_as_float(w << 16); }
; __device__ __forceinline__ float bfhi(unsigned w) { return __uint_as_float(w & 0xffff0000u); }
; template <bool F32OUT> __device__ __forceinline__ void norm_rows16(const bf16_t* X, const float* __restrict__ g, void* out, int rows) {
;     ...
;     while (row < rend) {
;         const int nrow = row + GWx; u32x4 xn[4];
;         if (nrow < rend) {
; #pragma unroll
;             for (int i = 0; i < 4; ++i) xn[i] = *(const u32x4*)(X + (size_t)nrow * DM + 8 * lane + 512 * i); }
;         float v[4][8]; float ss = 0.f;
; #pragma unroll
;         for (int i = 0; i < 4; ++i) { v[i][0] = bflo(x[i].x); v[i][1] = bfhi(x[i].x); v[i][2] = bflo(x[i].y); v[i][3] = bfhi(x[i].y); v[i][4] = bflo(x[i].z); v[i][5] = bfhi(x[i].z); v[i][6] = bflo(x[i].w); v[i][7] = bfhi(x[i].w);
; #pragma unroll
;             for (int e = 0; e < 8; ++e) ss += v[i][e] * v[i][e]; }
;         ss = wave_sum(ss);
;         const float rstd = rsqrtf(ss * (1.0f / DM) + 1e-6f);
; #pragma unroll
;         for (int i = 0; i < 4; ++i) {
;             const float o0 = v[i][0] * rstd * ga[i].x, o1 = v[i][1] * rstd * ga[i].y, o2 = v[i][2] * rstd * ga[i].z, o3 = v[i][3] * rstd * ga[i].w;
;             const float o4 = v[i][4] * rstd * gb[i].x, o5 = v[i][5] * rstd * gb[i].y, o6 = v[i][6] * rstd * gb[i].z, o7 = v[i][7] * rstd * gb[i].w;
;             if (F32OUT) { float* op = (float*)out + (size_t)row * DM + 8 * lane + 512 * i; *(float4*)op = make_float4(o0, o1, o2, o3); *(float4*)(op + 4) = make_float4(o4, o5, o6, o7); }
;             else { u32x4 w; w.x = cvt_pk_bf16(o0, o1); w.y = cvt_pk_bf16(o2, o3); w.z = cvt_pk_bf16(o4, o5); w.w = cvt_pk_bf16(o6, o7); *(u32x4*)((bf16_t*)out + (size_t)row * DM + 8 * lane + 512 * i) = w; }
;         }
; #pragma unroll
;         for (int i = 0; i < 4; ++i) x[i] = xn[i];
;         row = nrow;
;     }
.LBB0_2113:
	v_lshlrev_b32_e32 v76, 16, v60
	v_and_b32_e32 v77, 0xffff0000, v60
	v_pk_mul_f32 v[78:79], v[76:77], v[76:77]
	v_lshlrev_b32_e32 v60, 16, v61
	v_and_b32_e32 v61, 0xffff0000, v61
	v_pk_mul_f32 v[80:81], v[60:61], v[60:61]
	v_add_f32_e32 v75, v78, v79
	v_lshlrev_b32_e32 v82, 16, v62
	v_and_b32_e32 v83, 0xffff0000, v62
	v_add_f32_e32 v75, v80, v75
	v_pk_mul_f32 v[84:85], v[82:83], v[82:83]
	v_add_f32_e32 v75, v81, v75
	v_lshlrev_b32_e32 v62, 16, v63
	v_and_b32_e32 v63, 0xffff0000, v63
	v_add_f32_e32 v75, v84, v75
	v_pk_mul_f32 v[86:87], v[62:63], v[62:63]
	v_add_f32_e32 v75, v85, v75
	v_lshlrev_b32_e32 v88, 16, v56
	v_and_b32_e32 v89, 0xffff0000, v56
	v_add_f32_e32 v75, v86, v75
	v_pk_mul_f32 v[90:91], v[88:89], v[88:89]
	v_add_f32_e32 v75, v87, v75
	v_lshlrev_b32_e32 v56, 16, v57
	v_and_b32_e32 v57, 0xffff0000, v57
	v_add_f32_e32 v75, v90, v75
	v_pk_mul_f32 v[92:93], v[56:57], v[56:57]
	v_add_f32_e32 v75, v91, v75
	v_lshlrev_b32_e32 v94, 16, v58
	v_and_b32_e32 v95, 0xffff0000, v58
	v_add_f32_e32 v75, v92, v75
	v_pk_mul_f32 v[96:97], v[94:95], v[94:95]
	v_add_f32_e32 v75, v93, v75
	v_lshlrev_b32_e32 v58, 16, v59
	v_and_b32_e32 v59, 0xffff0000, v59
	v_add_f32_e32 v75, v96, v75
	v_pk_mul_f32 v[98:99], v[58:59], v[58:59]
	v_add_f32_e32 v75, v97, v75
	v_lshlrev_b32_e32 v100, 16, v52
	v_and_b32_e32 v101, 0xffff0000, v52
	v_add_f32_e32 v75, v98, v75
	v_pk_mul_f32 v[102:103], v[100:101], v[100:101]
	v_add_f32_e32 v75, v99, v75
	v_lshlrev_b32_e32 v104, 16, v53
	v_and_b32_e32 v105, 0xffff0000, v53
	v_add_f32_e32 v75, v102, v75
	v_pk_mul_f32 v[52:53], v[104:105], v[104:105]
	v_add_f32_e32 v75, v103, v75
	v_lshlrev_b32_e32 v106, 16, v54
	v_and_b32_e32 v107, 0xffff0000, v54
	v_add_f32_e32 v52, v52, v75
	v_pk_mul_f32 v[108:109], v[106:107], v[106:107]
	v_add_f32_e32 v52, v53, v52
	v_lshlrev_b32_e32 v110, 16, v55
	v_and_b32_e32 v111, 0xffff0000, v55
	v_add_f32_e32 v52, v108, v52
	v_pk_mul_f32 v[54:55], v[110:111], v[110:111]
	v_add_f32_e32 v52, v109, v52
	v_lshlrev_b32_e32 v112, 16, v48
	v_and_b32_e32 v113, 0xffff0000, v48
	v_add_f32_e32 v52, v54, v52
	v_pk_mul_f32 v[114:115], v[112:113], v[112:113]
	v_add_f32_e32 v52, v55, v52
	v_lshlrev_b32_e32 v116, 16, v49
	v_and_b32_e32 v117, 0xffff0000, v49
	v_add_f32_e32 v52, v114, v52
	v_pk_mul_f32 v[48:49], v[116:117], v[116:117]
	v_add_f32_e32 v52, v115, v52
	v_lshlrev_b32_e32 v118, 16, v50
	v_and_b32_e32 v119, 0xffff0000, v50
	v_add_f32_e32 v48, v48, v52
	v_pk_mul_f32 v[120:121], v[118:119], v[118:119]
	v_add_f32_e32 v48, v49, v48
	v_lshlrev_b32_e32 v122, 16, v51
	v_and_b32_e32 v123, 0xffff0000, v51
	v_add_f32_e32 v48, v120, v48
	v_pk_mul_f32 v[50:51], v[122:123], v[122:123]
	v_add_f32_e32 v48, v121, v48
	v_add_f32_e32 v48, v50, v48
	v_add_f32_e32 v48, v51, v48
	ds_bpermute_b32 v49, v68, v48
	v_lshl_add_u64 v[66:67], v[66:67], 0, s[4:5]
	s_waitcnt lgkmcnt(0)
	v_add_f32_e32 v48, v48, v49
	ds_bpermute_b32 v49, v69, v48
	s_waitcnt lgkmcnt(0)
	v_add_f32_e32 v48, v48, v49
	ds_bpermute_b32 v49, v70, v48
	s_waitcnt lgkmcnt(0)
	v_add_f32_e32 v48, v48, v49
	ds_bpermute_b32 v49, v71, v48
	s_waitcnt lgkmcnt(0)
	v_add_f32_e32 v48, v48, v49
	ds_bpermute_b32 v49, v72, v48
	s_waitcnt lgkmcnt(0)
	v_add_f32_e32 v48, v48, v49
	ds_bpermute_b32 v49, v73, v48
	s_waitcnt lgkmcnt(0)
	v_add_f32_e32 v48, v48, v49
	v_fmamk_f32 v48, v48, 0x3a000000, v74
	v_mul_f32_e32 v49, 0x4b800000, v48
	v_cmp_gt_f32_e32 vcc, s1, v48
	s_nop 1
	v_cndmask_b32_e32 v48, v48, v49, vcc
	v_rsq_f32_e32 v48, v48
	s_nop 0
	v_mul_f32_e32 v49, 0x45800000, v48
	v_cndmask_b32_e32 v78, v48, v49, vcc
	v_pk_mul_f32 v[48:49], v[78:79], v[76:77] op_sel_hi:[0,1]
	v_pk_mul_f32 v[50:51], v[78:79], v[60:61] op_sel_hi:[0,1]
	v_pk_mul_f32 v[52:53], v[78:79], v[82:83] op_sel_hi:[0,1]
	v_pk_mul_f32 v[54:55], v[78:79], v[62:63] op_sel_hi:[0,1]
	v_pk_mul_f32 v[48:49], v[8:9], v[48:49]
	v_pk_mul_f32 v[50:51], v[10:11], v[50:51]
	v_pk_mul_f32 v[52:53], v[4:5], v[52:53]
	v_pk_mul_f32 v[54:55], v[6:7], v[54:55]
	global_store_dwordx4 v[64:65], v[48:51], off offset:-4096
	global_store_dwordx4 v[64:65], v[52:55], off offset:-4080
	s_andn2_b64 vcc, exec, s[6:7]
	v_pk_mul_f32 v[48:49], v[78:79], v[88:89] op_sel_hi:[0,1]
	v_pk_mul_f32 v[50:51], v[78:79], v[56:57] op_sel_hi:[0,1]
	v_pk_mul_f32 v[52:53], v[78:79], v[94:95] op_sel_hi:[0,1]
	v_pk_mul_f32 v[54:55], v[78:79], v[58:59] op_sel_hi:[0,1]
	v_pk_mul_f32 v[48:49], v[16:17], v[48:49]
	v_pk_mul_f32 v[50:51], v[18:19], v[50:51]
	v_pk_mul_f32 v[52:53], v[12:13], v[52:53]
	v_pk_mul_f32 v[54:55], v[14:15], v[54:55]
	global_store_dwordx4 v[64:65], v[48:51], off offset:-2048
	global_store_dwordx4 v[64:65], v[52:55], off offset:-2032
	s_waitcnt vmcnt(4)
	v_mov_b32_e32 v60, v0
	v_pk_mul_f32 v[48:49], v[78:79], v[100:101] op_sel_hi:[0,1]
	v_pk_mul_f32 v[50:51], v[78:79], v[104:105] op_sel_hi:[0,1]
	v_pk_mul_f32 v[52:53], v[78:79], v[106:107] op_sel_hi:[0,1]
	v_pk_mul_f32 v[54:55], v[78:79], v[110:111] op_sel_hi:[0,1]
	v_pk_mul_f32 v[48:49], v[20:21], v[48:49]
	v_pk_mul_f32 v[50:51], v[22:23], v[50:51]
	v_pk_mul_f32 v[52:53], v[24:25], v[52:53]
	v_pk_mul_f32 v[54:55], v[26:27], v[54:55]
	global_store_dwordx4 v[64:65], v[48:51], off
	global_store_dwordx4 v[64:65], v[52:55], off offset:16
	v_mov_b32_e32 v61, v1
	v_pk_mul_f32 v[48:49], v[78:79], v[112:113] op_sel_hi:[0,1]
	v_pk_mul_f32 v[50:51], v[78:79], v[116:117] op_sel_hi:[0,1]
	v_pk_mul_f32 v[52:53], v[78:79], v[118:119] op_sel_hi:[0,1]
	v_pk_mul_f32 v[54:55], v[78:79], v[122:123] op_sel_hi:[0,1]
	v_pk_mul_f32 v[48:49], v[28:29], v[48:49]
	v_pk_mul_f32 v[50:51], v[30:31], v[50:51]
	v_pk_mul_f32 v[52:53], v[32:33], v[52:53]
	v_pk_mul_f32 v[54:55], v[34:35], v[54:55]
	global_store_dwordx4 v[64:65], v[48:51], off offset:2048
	global_store_dwordx4 v[64:65], v[52:55], off offset:2064
	v_lshl_add_u64 v[64:65], v[64:65], 0, s[2:3]
	v_mov_b32_e32 v62, v2
	v_mov_b32_e32 v63, v3
	v_mov_b32_e32 v56, v36
	v_mov_b32_e32 v57, v37
	v_mov_b32_e32 v58, v38
	v_mov_b32_e32 v59, v39
	v_mov_b32_e32 v52, v40
	v_mov_b32_e32 v53, v41
	v_mov_b32_e32 v54, v42
	v_mov_b32_e32 v55, v43
	v_mov_b32_e32 v48, v44
	v_mov_b32_e32 v49, v45
	v_mov_b32_e32 v50, v46
	v_mov_b32_e32 v51, v47
	s_cbranch_vccz .LBB0_2116
